# P6 epilogue part 1: counted waits per row group for the first x1 batch
# baseline (speedup 1.0000x reference)
;     __device__ __forceinline__ void operator()(f32x4 (&acc)[2][2][4][2], const Unit& u, int wr, int wc, int fr, int fq) const {
;     ...
;         for (int ai = 0; ai < 2; ++ai) {
;             u32x4 xv[4][2];
; #pragma unroll
;             for (int m = 0; m < 4; ++m)
; #pragma unroll
;                 for (int bj = 0; bj < 2; ++bj) { const size_t off = (size_t)(row0 + ai * HALF + m * 16) * DM + col0 + bj * HALF; xv[m][bj] = *(const u32x4*)(xb + off); }
; #pragma unroll
;             for (int m = 0; m < 4; ++m) { const size_t r = (size_t)(row0 + ai * HALF + m * 16); float ss = 0.f;
; #pragma unroll
;                 for (int bj = 0; bj < 2; ++bj) { const u32x4 xw = xv[m][bj];
;                     const f32x4 x0 = {bf_lo(xw.x), bf_hi(xw.x), bf_lo(xw.y), bf_hi(xw.y)}, x1 = {bf_lo(xw.z), bf_hi(xw.z), bf_lo(xw.w), bf_hi(xw.w)};
;                     const f32x4 v0 = acc[ai][bj][m][0] + x0, v1 = acc[ai][bj][m][1] + x1; acc[ai][bj][m][0] = v0; acc[ai][bj][m][1] = v1;
;                     ss += (v0[0] * v0[0] + v0[1] * v0[1]) + (v0[2] * v0[2] + v0[3] * v0[3]) + (v1[0] * v1[0] + v1[1] * v1[1]) + (v1[2] * v1[2] + v1[3] * v1[3]); }
;                 ss += __shfl_xor(ss, 16); ss += __shfl_xor(ss, 32);
;                 if (fq == 0) __hip_atomic_store(ssq + r * 16 + u.pn * 4 + wc, ss, __ATOMIC_RELAXED, __HIP_MEMORY_SCOPE_AGENT); }
.Lmy_ab_p6:
	v_and_b32_e32 v189, 64, v204
	v_xor_b32_e32 v188, 16, v204
	v_add_u32_e32 v207, 64, v189
	v_cmp_lt_i32_e32 vcc, v188, v207
	s_lshl_b32 s40, s6, 2
	s_ashr_i32 s41, s40, 31
	v_cndmask_b32_e32 v188, v204, v188, vcc
	v_lshlrev_b32_e32 v206, 2, v188
	s_waitcnt vmcnt(14)
	v_lshlrev_b32_e32 v188, 16, v180
	v_and_b32_e32 v189, 0xffff0000, v180
	v_lshlrev_b32_e32 v180, 16, v181
	v_and_b32_e32 v181, 0xffff0000, v181
	v_lshlrev_b32_e32 v192, 16, v184
	v_and_b32_e32 v193, 0xffff0000, v184
	v_lshlrev_b32_e32 v184, 16, v185
	v_and_b32_e32 v185, 0xffff0000, v185
	v_lshlrev_b32_e32 v190, 16, v182
	v_and_b32_e32 v191, 0xffff0000, v182
	v_lshlrev_b32_e32 v194, 16, v186
	v_and_b32_e32 v195, 0xffff0000, v186
	v_pk_add_f32 v[126:127], v[126:127], v[180:181]
	v_pk_add_f32 v[124:125], v[124:125], v[188:189]
	v_pk_add_f32 v[118:119], v[118:119], v[184:185]
	v_pk_add_f32 v[116:117], v[116:117], v[192:193]
	v_lshlrev_b32_e32 v182, 16, v183
	v_and_b32_e32 v183, 0xffff0000, v183
	v_lshlrev_b32_e32 v186, 16, v187
	v_and_b32_e32 v187, 0xffff0000, v187
	v_pk_add_f32 v[120:121], v[120:121], v[190:191]
	v_pk_add_f32 v[112:113], v[112:113], v[194:195]
	v_mul_f32_e32 v180, v125, v125
	v_mul_f32_e32 v181, v127, v127
	v_mul_f32_e32 v184, v117, v117
	v_mul_f32_e32 v185, v119, v119
	v_pk_add_f32 v[122:123], v[122:123], v[182:183]
	v_pk_add_f32 v[114:115], v[114:115], v[186:187]
	v_mul_f32_e32 v182, v121, v121
	v_mul_f32_e32 v186, v113, v113
	v_fmac_f32_e32 v180, v124, v124
	v_fmac_f32_e32 v181, v126, v126
	v_fmac_f32_e32 v184, v116, v116
	v_fmac_f32_e32 v185, v118, v118
	v_mul_f32_e32 v183, v123, v123
	v_mul_f32_e32 v187, v115, v115
	v_fmac_f32_e32 v182, v120, v120
	v_fmac_f32_e32 v186, v112, v112
	v_add_f32_e32 v180, v180, v181
	v_add_f32_e32 v181, v184, v185
	v_fmac_f32_e32 v183, v122, v122
	v_fmac_f32_e32 v187, v114, v114
	v_add_f32_e32 v180, v182, v180
	v_add_f32_e32 v181, v186, v181
	v_add_f32_e32 v180, v183, v180
	v_add_f32_e32 v181, v187, v181
	v_add_f32_e32 v180, v180, v181
	ds_bpermute_b32 v181, v206, v180
	v_xor_b32_e32 v182, 32, v204
	v_cmp_lt_i32_e32 vcc, v182, v207
	v_lshlrev_b64 v[188:189], 6, v[176:177]
	s_waitcnt lgkmcnt(0)
	v_add_f32_e32 v180, v180, v181
	v_cndmask_b32_e32 v182, v204, v182, vcc
	v_lshlrev_b32_e32 v207, 2, v182
	ds_bpermute_b32 v181, v207, v180
	s_and_saveexec_b64 s[42:43], s[0:1]
	s_cbranch_execz .LBB0_432
	s_waitcnt lgkmcnt(0)
	v_add_f32_e32 v182, v180, v181
	v_lshl_add_u64 v[180:181], s[10:11], 0, v[188:189]
	v_lshl_add_u64 v[180:181], s[40:41], 2, v[180:181]
	s_lshl_b32 s6, s53, 2
	v_lshl_add_u64 v[180:181], v[180:181], 0, s[6:7]
	global_store_dword v[180:181], v182, off sc1
.LBB0_432:
	s_or_b64 exec, exec, s[42:43]
	s_waitcnt vmcnt(13)
	v_lshlrev_b32_e32 v180, 16, v148
	s_waitcnt lgkmcnt(0)
	v_and_b32_e32 v181, 0xffff0000, v148
	v_lshlrev_b32_e32 v148, 16, v149
	v_and_b32_e32 v149, 0xffff0000, v149
	v_pk_add_f32 v[110:111], v[110:111], v[148:149]
	v_pk_add_f32 v[108:109], v[108:109], v[180:181]
	v_lshlrev_b32_e32 v182, 16, v150
	v_and_b32_e32 v183, 0xffff0000, v150
	v_mul_f32_e32 v148, v109, v109
	v_mul_f32_e32 v149, v111, v111
	v_pk_add_f32 v[104:105], v[104:105], v[182:183]
	v_fmac_f32_e32 v148, v108, v108
	v_fmac_f32_e32 v149, v110, v110
	v_lshlrev_b32_e32 v150, 16, v151
	v_and_b32_e32 v151, 0xffff0000, v151
	v_add_f32_e32 v148, v148, v149
	v_mul_f32_e32 v149, v105, v105
	v_pk_add_f32 v[106:107], v[106:107], v[150:151]
	v_fmac_f32_e32 v149, v104, v104
	v_add_f32_e32 v148, v149, v148
	v_mul_f32_e32 v149, v107, v107
	v_fmac_f32_e32 v149, v106, v106
	v_add_f32_e32 v182, v149, v148
	v_lshlrev_b32_e32 v148, 16, v144
	v_and_b32_e32 v149, 0xffff0000, v144
	v_lshlrev_b32_e32 v144, 16, v145
	v_and_b32_e32 v145, 0xffff0000, v145
	v_lshlrev_b32_e32 v150, 16, v146
	v_and_b32_e32 v151, 0xffff0000, v146
	v_lshlrev_b32_e32 v180, 16, v147
	v_and_b32_e32 v181, 0xffff0000, v147
	v_pk_add_f32 v[144:145], v[102:103], v[144:145]
	v_pk_add_f32 v[146:147], v[100:101], v[148:149]
	v_pk_add_f32 v[150:151], v[96:97], v[150:151]
	v_mul_f32_e32 v96, v147, v147
	v_mul_f32_e32 v97, v145, v145
	v_fmac_f32_e32 v96, v146, v146
	v_fmac_f32_e32 v97, v144, v144
	v_add_f32_e32 v96, v96, v97
	v_mul_f32_e32 v97, v151, v151
	v_pk_add_f32 v[148:149], v[98:99], v[180:181]
	v_fmac_f32_e32 v97, v150, v150
	v_add_f32_e32 v96, v97, v96
	v_mul_f32_e32 v97, v149, v149
	v_fmac_f32_e32 v97, v148, v148
	v_add_f32_e32 v96, v97, v96
	v_add_f32_e32 v96, v182, v96
	ds_bpermute_b32 v97, v206, v96
	v_lshlrev_b64 v[190:191], 6, v[174:175]
	s_waitcnt lgkmcnt(0)
	v_add_f32_e32 v96, v96, v97
	ds_bpermute_b32 v97, v207, v96
	s_and_saveexec_b64 s[42:43], s[0:1]
	s_cbranch_execz .LBB0_434
	s_waitcnt lgkmcnt(0)
	v_add_f32_e32 v98, v96, v97
	v_lshl_add_u64 v[96:97], s[10:11], 0, v[190:191]
	v_lshl_add_u64 v[96:97], s[40:41], 2, v[96:97]
	s_lshl_b32 s6, s53, 2
	v_lshl_add_u64 v[96:97], v[96:97], 0, s[6:7]
	global_store_dword v[96:97], v98, off sc1
;     __device__ __forceinline__ void operator()(f32x4 (&acc)[2][2][4][2], const Unit& u, int wr, int wc, int fr, int fq) const {
;     ...
;             for (int m = 0; m < 4; ++m) { const size_t r = (size_t)(row0 + ai * HALF + m * 16); float ss = 0.f;
; #pragma unroll
;                 for (int bj = 0; bj < 2; ++bj) { const u32x4 xw = xv[m][bj];
;                     const f32x4 x0 = {bf_lo(xw.x), bf_hi(xw.x), bf_lo(xw.y), bf_hi(xw.y)}, x1 = {bf_lo(xw.z), bf_hi(xw.z), bf_lo(xw.w), bf_hi(xw.w)};
;                     const f32x4 v0 = acc[ai][bj][m][0] + x0, v1 = acc[ai][bj][m][1] + x1; acc[ai][bj][m][0] = v0; acc[ai][bj][m][1] = v1;
;                     ss += (v0[0] * v0[0] + v0[1] * v0[1]) + (v0[2] * v0[2] + v0[3] * v0[3]) + (v1[0] * v1[0] + v1[1] * v1[1]) + (v1[2] * v1[2] + v1[3] * v1[3]); }
;                 ss += __shfl_xor(ss, 16); ss += __shfl_xor(ss, 32);
;                 if (fq == 0) __hip_atomic_store(ssq + r * 16 + u.pn * 4 + wc, ss, __ATOMIC_RELAXED, __HIP_MEMORY_SCOPE_AGENT); }
.LBB0_434:
	s_or_b64 exec, exec, s[42:43]
	s_waitcnt vmcnt(12)
	v_lshlrev_b32_e32 v96, 16, v140
	s_waitcnt lgkmcnt(0)
	v_and_b32_e32 v97, 0xffff0000, v140
	v_lshlrev_b32_e32 v98, 16, v141
	v_and_b32_e32 v99, 0xffff0000, v141
	v_lshlrev_b32_e32 v100, 16, v142
	v_and_b32_e32 v101, 0xffff0000, v142
	v_lshlrev_b32_e32 v102, 16, v143
	v_and_b32_e32 v103, 0xffff0000, v143
	v_pk_add_f32 v[94:95], v[94:95], v[98:99]
	v_pk_add_f32 v[96:97], v[92:93], v[96:97]
	v_pk_add_f32 v[98:99], v[90:91], v[102:103]
	v_pk_add_f32 v[102:103], v[88:89], v[100:101]
	v_mul_f32_e32 v88, v97, v97
	v_mul_f32_e32 v89, v95, v95
	v_fmac_f32_e32 v88, v96, v96
	v_fmac_f32_e32 v89, v94, v94
	v_add_f32_e32 v88, v88, v89
	v_mul_f32_e32 v89, v103, v103
	v_fmac_f32_e32 v89, v102, v102
	v_add_f32_e32 v88, v89, v88
	v_mul_f32_e32 v89, v99, v99
	v_fmac_f32_e32 v89, v98, v98
	v_add_f32_e32 v182, v89, v88
	v_lshlrev_b32_e32 v88, 16, v136
	v_and_b32_e32 v89, 0xffff0000, v136
	v_lshlrev_b32_e32 v90, 16, v137
	v_and_b32_e32 v91, 0xffff0000, v137
	v_lshlrev_b32_e32 v92, 16, v138
	v_and_b32_e32 v93, 0xffff0000, v138
	v_lshlrev_b32_e32 v100, 16, v139
	v_and_b32_e32 v101, 0xffff0000, v139
	v_pk_add_f32 v[138:139], v[86:87], v[90:91]
	v_pk_add_f32 v[140:141], v[84:85], v[88:89]
	v_pk_add_f32 v[180:181], v[80:81], v[92:93]
	v_mul_f32_e32 v80, v141, v141
	v_mul_f32_e32 v81, v139, v139
	v_fmac_f32_e32 v80, v140, v140
	v_fmac_f32_e32 v81, v138, v138
	v_add_f32_e32 v80, v80, v81
	v_mul_f32_e32 v81, v181, v181
	v_pk_add_f32 v[142:143], v[82:83], v[100:101]
	v_fmac_f32_e32 v81, v180, v180
	v_add_f32_e32 v80, v81, v80
	v_mul_f32_e32 v81, v143, v143
	v_fmac_f32_e32 v81, v142, v142
	v_add_f32_e32 v80, v81, v80
	v_add_f32_e32 v80, v182, v80
	ds_bpermute_b32 v81, v206, v80
	v_lshlrev_b64 v[192:193], 6, v[172:173]
	s_waitcnt lgkmcnt(0)
	v_add_f32_e32 v80, v80, v81
	ds_bpermute_b32 v81, v207, v80
	s_and_saveexec_b64 s[42:43], s[0:1]
	s_cbranch_execz .LBB0_436
	s_waitcnt lgkmcnt(0)
	v_add_f32_e32 v82, v80, v81
	v_lshl_add_u64 v[80:81], s[10:11], 0, v[192:193]
	v_lshl_add_u64 v[80:81], s[40:41], 2, v[80:81]
	s_lshl_b32 s6, s53, 2
	v_lshl_add_u64 v[80:81], v[80:81], 0, s[6:7]
	global_store_dword v[80:81], v82, off sc1
.LBB0_436:
	s_or_b64 exec, exec, s[42:43]
	s_waitcnt vmcnt(11)
	v_lshlrev_b32_e32 v80, 16, v132
	s_waitcnt lgkmcnt(0)
	v_and_b32_e32 v81, 0xffff0000, v132
	v_lshlrev_b32_e32 v82, 16, v133
	v_and_b32_e32 v83, 0xffff0000, v133
	v_lshlrev_b32_e32 v84, 16, v134
	v_and_b32_e32 v85, 0xffff0000, v134
	v_pk_add_f32 v[100:101], v[78:79], v[82:83]
	v_pk_add_f32 v[132:133], v[76:77], v[80:81]
	v_pk_add_f32 v[136:137], v[72:73], v[84:85]
	v_mul_f32_e32 v72, v133, v133
	v_mul_f32_e32 v73, v101, v101
	v_fmac_f32_e32 v72, v132, v132
	v_fmac_f32_e32 v73, v100, v100
	v_lshlrev_b32_e32 v86, 16, v135
	v_and_b32_e32 v87, 0xffff0000, v135
	v_add_f32_e32 v72, v72, v73
	v_mul_f32_e32 v73, v137, v137
	v_pk_add_f32 v[134:135], v[74:75], v[86:87]
	v_fmac_f32_e32 v73, v136, v136
	v_add_f32_e32 v72, v73, v72
	v_mul_f32_e32 v73, v135, v135
	v_fmac_f32_e32 v73, v134, v134
	v_add_f32_e32 v80, v73, v72
	v_lshlrev_b32_e32 v72, 16, v128
	v_and_b32_e32 v73, 0xffff0000, v128
	v_lshlrev_b32_e32 v74, 16, v129
	v_and_b32_e32 v75, 0xffff0000, v129
	v_lshlrev_b32_e32 v76, 16, v130
	v_and_b32_e32 v77, 0xffff0000, v130
	v_lshlrev_b32_e32 v78, 16, v131
	v_and_b32_e32 v79, 0xffff0000, v131
	v_pk_add_f32 v[128:129], v[70:71], v[74:75]
	v_pk_add_f32 v[130:131], v[68:69], v[72:73]
	v_pk_add_f32 v[184:185], v[64:65], v[76:77]
	v_mul_f32_e32 v64, v131, v131
	v_mul_f32_e32 v65, v129, v129
	v_fmac_f32_e32 v64, v130, v130
	v_fmac_f32_e32 v65, v128, v128
	v_add_f32_e32 v64, v64, v65
	v_mul_f32_e32 v65, v185, v185
	v_pk_add_f32 v[182:183], v[66:67], v[78:79]
	v_fmac_f32_e32 v65, v184, v184
	v_add_f32_e32 v64, v65, v64
	v_mul_f32_e32 v65, v183, v183
	v_fmac_f32_e32 v65, v182, v182
	v_add_f32_e32 v64, v65, v64
	v_add_f32_e32 v64, v80, v64
	ds_bpermute_b32 v65, v206, v64
	v_lshlrev_b64 v[194:195], 6, v[170:171]
	s_waitcnt lgkmcnt(0)
	v_add_f32_e32 v64, v64, v65
	ds_bpermute_b32 v65, v207, v64
	s_and_saveexec_b64 s[42:43], s[0:1]
	s_cbranch_execz .LBB0_438
	s_waitcnt lgkmcnt(0)
	v_add_f32_e32 v66, v64, v65
	v_lshl_add_u64 v[64:65], s[10:11], 0, v[194:195]
	v_lshl_add_u64 v[64:65], s[40:41], 2, v[64:65]
	s_lshl_b32 s6, s53, 2
	v_lshl_add_u64 v[64:65], v[64:65], 0, s[6:7]
	global_store_dword v[64:65], v66, off sc1
